# prep HGRN main loop: its 16 row loads (serialized by hipcc in 5 dependent round trips per iteration) hoisted to the loop top in one batch, single wait
# speedup vs baseline: 1.0084x; 1.0084x over previous
; DI bf16_t f2bf(float x) { unsigned u = __float_as_uint(x); u += 0x7fffu + ((u >> 16) & 1u); return (bf16_t)(u >> 16); }
; DI float bf2f(bf16_t b) { return __uint_as_float(((unsigned)b) << 16); }
; DI float sigmoidf_(float x) { return 1.f / (1.f + __expf(-x)); }
; DI void phase_prep(const P& p, int layer, float* ldsf) {
;     ...
;       for (int n8 = 0; n8 < 4; ++n8) {
;         float kq8[8];
;         bf16_t fl_[8], gq_[8];
; #pragma unroll
;         for (int j = 0; j < 8; ++j) { const bf16_t* row = proj + (long)(t0 + n8 * 8 + j) * NPJ; fl_[j] = row[4096 + tid]; gq_[j] = row[3584 + tid]; }
; #pragma unroll
;         for (int j = 0; j < 8; ++j) {
;           const int n = n8 * 8 + j;
;           float fl = bf2f(fl_[j]);
;           float f = lbv + (1.f - lbv) * sigmoidf_(fl);
;           G += __logf(fmaxf(f, 1e-6f));
;           float kk = 1.f - f;
;           qp[(long)(t0 + n) * 1024 + 512 + tid] = f2bf(bf2f(gq_[j]) * SCALE * __expf(G));
;           kp[(long)(t0 + n) * 1024 + 512 + tid] = f2bf(kk * __expf(fminf(-G, 80.f)));
;           kq8[j] = kk * __expf(G31 - G);
.LBB0_360:
	s_nop 0
	v_lshl_add_u64 v[190:191], s[46:47], 0, v[42:43]
	v_add_co_u32_e32 v192, vcc, s3, v190
	s_nop 1
	v_addc_co_u32_e32 v193, vcc, 0, v191, vcc
	global_load_ushort v174, v[192:193], off
	v_lshl_add_u64 v[190:191], s[46:47], 0, v[44:45]
	v_add_co_u32_e32 v192, vcc, s4, v190
	s_nop 1
	v_addc_co_u32_e32 v193, vcc, 0, v191, vcc
	global_load_ushort v175, v[192:193], off offset:3072
	v_lshl_add_u64 v[190:191], s[46:47], 0, v[46:47]
	v_add_co_u32_e32 v192, vcc, s3, v190
	s_nop 1
	v_addc_co_u32_e32 v193, vcc, 0, v191, vcc
	global_load_ushort v176, v[192:193], off
	v_lshl_add_u64 v[190:191], s[46:47], 0, v[42:43]
	v_add_co_u32_e32 v192, vcc, s4, v190
	s_nop 1
	v_addc_co_u32_e32 v193, vcc, 0, v191, vcc
	global_load_ushort v177, v[192:193], off offset:3072
	v_lshl_add_u64 v[190:191], s[46:47], 0, v[44:45]
	v_add_co_u32_e32 v192, vcc, s3, v190
	s_nop 1
	v_addc_co_u32_e32 v193, vcc, 0, v191, vcc
	global_load_ushort v178, v[192:193], off
	v_lshl_add_u64 v[190:191], s[46:47], 0, v[48:49]
	v_add_co_u32_e32 v192, vcc, s3, v190
	s_nop 1
	v_addc_co_u32_e32 v193, vcc, 0, v191, vcc
	global_load_ushort v179, v[192:193], off
	v_lshl_add_u64 v[190:191], s[46:47], 0, v[48:49]
	v_add_co_u32_e32 v192, vcc, s4, v190
	s_nop 1
	v_addc_co_u32_e32 v193, vcc, 0, v191, vcc
	global_load_ushort v180, v[192:193], off offset:3072
	v_lshl_add_u64 v[190:191], s[46:47], 0, v[46:47]
	v_add_co_u32_e32 v192, vcc, s4, v190
	s_nop 1
	v_addc_co_u32_e32 v193, vcc, 0, v191, vcc
	global_load_ushort v181, v[192:193], off offset:3072
	v_lshl_add_u64 v[190:191], s[46:47], 0, v[50:51]
	v_add_co_u32_e32 v192, vcc, s3, v190
	s_nop 1
	v_addc_co_u32_e32 v193, vcc, 0, v191, vcc
	global_load_ushort v182, v[192:193], off
	v_lshl_add_u64 v[190:191], s[46:47], 0, v[50:51]
	v_add_co_u32_e32 v192, vcc, s4, v190
	s_nop 1
	v_addc_co_u32_e32 v193, vcc, 0, v191, vcc
	global_load_ushort v183, v[192:193], off offset:3072
	v_lshl_add_u64 v[190:191], s[46:47], 0, v[52:53]
	v_add_co_u32_e32 v192, vcc, s3, v190
	s_nop 1
	v_addc_co_u32_e32 v193, vcc, 0, v191, vcc
	global_load_ushort v184, v[192:193], off
	v_lshl_add_u64 v[190:191], s[46:47], 0, v[52:53]
	v_add_co_u32_e32 v192, vcc, s4, v190
	s_nop 1
	v_addc_co_u32_e32 v193, vcc, 0, v191, vcc
	global_load_ushort v185, v[192:193], off offset:3072
	v_lshl_add_u64 v[190:191], s[46:47], 0, v[54:55]
	v_add_co_u32_e32 v192, vcc, s3, v190
	s_nop 1
	v_addc_co_u32_e32 v193, vcc, 0, v191, vcc
	global_load_ushort v186, v[192:193], off
	v_lshl_add_u64 v[190:191], s[46:47], 0, v[54:55]
	v_add_co_u32_e32 v192, vcc, s4, v190
	s_nop 1
	v_addc_co_u32_e32 v193, vcc, 0, v191, vcc
	global_load_ushort v187, v[192:193], off offset:3072
	v_lshl_add_u64 v[190:191], s[46:47], 0, v[56:57]
	v_add_co_u32_e32 v192, vcc, s3, v190
	s_nop 1
	v_addc_co_u32_e32 v193, vcc, 0, v191, vcc
	global_load_ushort v188, v[192:193], off
	v_lshl_add_u64 v[190:191], s[46:47], 0, v[56:57]
	v_add_co_u32_e32 v192, vcc, s4, v190
	s_nop 1
	v_addc_co_u32_e32 v193, vcc, 0, v191, vcc
	global_load_ushort v189, v[192:193], off offset:3072
	v_lshl_add_u64 v[58:59], s[46:47], 0, v[42:43]
	v_add_co_u32_e32 v60, vcc, s3, v58
	v_lshl_add_u64 v[62:63], s[46:47], 0, v[44:45]
	s_nop 0
	v_addc_co_u32_e32 v61, vcc, 0, v59, vcc
	v_add_co_u32_e32 v58, vcc, s4, v58
	v_lshl_add_u64 v[68:69], s[46:47], 0, v[46:47]
	s_nop 0
	v_addc_co_u32_e32 v59, vcc, 0, v59, vcc
	v_add_co_u32_e32 v64, vcc, s3, v62
	s_nop 0
	s_nop 3
	v_addc_co_u32_e32 v65, vcc, 0, v63, vcc
	v_add_co_u32_e32 v62, vcc, s4, v62
	v_lshl_add_u64 v[72:73], s[46:47], 0, v[48:49]
	s_nop 0
	v_addc_co_u32_e32 v63, vcc, 0, v63, vcc
	v_lshl_add_u64 v[80:81], s[46:47], 0, v[50:51]
	v_lshl_add_u64 v[78:79], s[46:47], 0, v[52:53]
	v_lshl_add_u64 v[76:77], s[46:47], 0, v[54:55]
	v_lshl_add_u64 v[70:71], s[46:47], 0, v[56:57]
	s_add_i32 s2, s2, -1
	v_lshl_add_u64 v[56:57], v[56:57], 0, s[86:87]
	v_lshl_add_u64 v[54:55], v[54:55], 0, s[86:87]
	v_lshl_add_u64 v[52:53], v[52:53], 0, s[86:87]
	v_lshl_add_u64 v[50:51], v[50:51], 0, s[86:87]
	v_lshl_add_u64 v[48:49], v[48:49], 0, s[86:87]
	v_lshl_add_u64 v[46:47], v[46:47], 0, s[86:87]
	v_lshl_add_u64 v[44:45], v[44:45], 0, s[86:87]
	v_lshl_add_u64 v[42:43], v[42:43], 0, s[86:87]
	s_cmp_eq_u32 s2, 0
	s_waitcnt vmcnt(0)
	v_lshlrev_b32_e32 v62, 16, v175
	v_mul_f32_e32 v129, 0x3db504f3, v62
	v_add_co_u32_e32 v62, vcc, s3, v68
	s_nop 1
	v_addc_co_u32_e32 v63, vcc, 0, v69, vcc
	v_lshlrev_b32_e32 v62, 16, v176
	v_mul_f32_e32 v62, 0xbfb8aa3b, v62
	v_exp_f32_e32 v66, v62
	v_add_co_u32_e32 v62, vcc, s4, v68
	s_nop 0
	s_nop 3
	v_addc_co_u32_e32 v63, vcc, 0, v69, vcc
	v_add_co_u32_e32 v68, vcc, s3, v72
	s_nop 0
	s_nop 3
	v_addc_co_u32_e32 v69, vcc, 0, v73, vcc
	v_add_co_u32_e32 v68, vcc, s4, v72
	v_lshlrev_b32_e32 v60, 16, v174
	s_nop 0
	v_addc_co_u32_e32 v69, vcc, 0, v73, vcc
	v_mul_f32_e32 v60, 0xbfb8aa3b, v60
	v_exp_f32_e32 v60, v60
	v_lshl_add_u64 v[64:65], s[46:47], 0, v[38:39]
	v_lshl_add_u64 v[72:73], s[46:47], 0, v[34:35]
	v_lshl_add_u64 v[34:35], v[34:35], 0, s[54:55]
	v_lshl_add_u64 v[38:39], v[38:39], 0, s[54:55]
	v_lshlrev_b32_e32 v58, 16, v177
	v_mul_f32_e32 v127, 0x3db504f3, v58
	v_lshl_add_u64 v[58:59], s[46:47], 0, v[40:41]
	v_lshl_add_u64 v[40:41], v[40:41], 0, s[54:55]
	v_lshlrev_b32_e32 v61, 16, v178
	v_mul_f32_e32 v61, 0xbfb8aa3b, v61
	v_exp_f32_e32 v61, v61
	v_lshlrev_b32_e32 v67, 16, v179
	v_mul_f32_e32 v67, 0xbfb8aa3b, v67
	v_exp_f32_e32 v67, v67
	v_pk_add_f32 v[60:61], v[60:61], 1.0 op_sel_hi:[1,0]
	v_lshlrev_b32_e32 v68, 16, v180
	v_mul_f32_e32 v133, 0x3db504f3, v68
	v_add_co_u32_e32 v68, vcc, s3, v80
	s_nop 0
	s_nop 3
	v_addc_co_u32_e32 v69, vcc, 0, v81, vcc
	v_lshlrev_b32_e32 v62, 16, v181
; DI bf16_t f2bf(float x) { unsigned u = __float_as_uint(x); u += 0x7fffu + ((u >> 16) & 1u); return (bf16_t)(u >> 16); }
; DI float bf2f(bf16_t b) { return __uint_as_float(((unsigned)b) << 16); }
; DI float sigmoidf_(float x) { return 1.f / (1.f + __expf(-x)); }
; DI void phase_prep(const P& p, int layer, float* ldsf) {
;     ...
;         for (int j = 0; j < 8; ++j) { const bf16_t* row = proj + (long)(t0 + n8 * 8 + j) * NPJ; fl_[j] = row[4096 + tid]; gq_[j] = row[3584 + tid]; }
; #pragma unroll
;         for (int j = 0; j < 8; ++j) {
;           const int n = n8 * 8 + j;
;           float fl = bf2f(fl_[j]);
;           float f = lbv + (1.f - lbv) * sigmoidf_(fl);
;           G += __logf(fmaxf(f, 1e-6f));
;           float kk = 1.f - f;
;           qp[(long)(t0 + n) * 1024 + 512 + tid] = f2bf(bf2f(gq_[j]) * SCALE * __expf(G));
;           kp[(long)(t0 + n) * 1024 + 512 + tid] = f2bf(kk * __expf(fminf(-G, 80.f)));
;           kq8[j] = kk * __expf(G31 - G);
	v_mul_f32_e32 v131, 0x3db504f3, v62
	v_lshl_add_u64 v[62:63], s[46:47], 0, v[36:37]
	v_lshl_add_u64 v[36:37], v[36:37], 0, s[54:55]
	v_lshlrev_b32_e32 v68, 16, v182
	v_mul_f32_e32 v68, 0xbfb8aa3b, v68
	v_exp_f32_e32 v74, v68
	v_add_co_u32_e32 v68, vcc, s4, v80
	s_nop 1
	v_addc_co_u32_e32 v69, vcc, 0, v81, vcc
	v_add_co_u32_e32 v80, vcc, s3, v78
	s_nop 0
	s_nop 3
	v_addc_co_u32_e32 v81, vcc, 0, v79, vcc
	v_add_co_u32_e32 v78, vcc, s4, v78
	s_nop 0
	s_nop 3
	v_addc_co_u32_e32 v79, vcc, 0, v79, vcc
	v_add_co_u32_e32 v80, vcc, s3, v76
	v_lshlrev_b32_e32 v75, 16, v184
	s_nop 3
	v_addc_co_u32_e32 v81, vcc, 0, v77, vcc
	v_add_co_u32_e32 v76, vcc, s4, v76
	s_nop 0
	s_nop 3
	v_addc_co_u32_e32 v77, vcc, 0, v77, vcc
	v_add_co_u32_e32 v170, vcc, s3, v70
	s_nop 0
	s_nop 3
	v_addc_co_u32_e32 v171, vcc, 0, v71, vcc
	v_add_co_u32_e32 v70, vcc, s4, v70
	s_nop 0
	s_nop 3
	v_addc_co_u32_e32 v71, vcc, 0, v71, vcc
	v_rcp_f32_e32 v143, v61
	s_nop 0
	v_mul_f32_e32 v61, 1.0, v143
	v_mul_f32_e32 v75, 0xbfb8aa3b, v75
	v_exp_f32_e32 v75, v75
	v_rcp_f32_e32 v143, v60
	s_nop 0
	v_mul_f32_e32 v60, 1.0, v143
	v_pk_fma_f32 v[60:61], v[6:7], v[60:61], v[4:5]
	v_lshlrev_b32_e32 v68, 16, v183
	v_max_f32_e32 v143, 0x358637bd, v60
	v_cmp_gt_f32_e32 vcc, s33, v143
	v_mul_f32_e32 v135, 0x3db504f3, v68
	v_lshl_add_u64 v[68:69], s[46:47], 0, v[32:33]
	v_cndmask_b32_e64 v145, 0, 32, vcc
	v_ldexp_f32 v143, v143, v145
	v_log_f32_e32 v143, v143
	v_lshlrev_b32_e32 v78, 16, v185
	v_mul_f32_e32 v137, 0x3db504f3, v78
	v_lshl_add_u64 v[78:79], s[46:47], 0, v[30:31]
	v_mul_f32_e32 v145, 0x3f317217, v143
	v_fma_f32 v145, v143, s79, -v145
	v_fmac_f32_e32 v145, 0x3377d1cf, v143
	v_fmac_f32_e32 v145, 0x3f317217, v143
	v_cmp_lt_f32_e64 s[0:1], |v143|, s73
	v_lshl_add_u64 v[170:171], s[46:47], 0, v[26:27]
	v_lshl_add_u64 v[26:27], v[26:27], 0, s[54:55]
	v_cndmask_b32_e64 v143, v143, v145, s[0:1]
	v_cndmask_b32_e32 v145, 0, v211, vcc
	v_sub_f32_e32 v143, v143, v145
	v_add_f32_e32 v3, v3, v143
	v_mul_f32_e32 v143, 0x3fb8aa3b, v3
	v_exp_f32_e32 v143, v143
	v_add_co_u32_e32 v172, vcc, s5, v58
	v_lshl_add_u64 v[30:31], v[30:31], 0, s[54:55]
	v_mul_f32_e32 v127, v127, v143
	v_bfe_u32 v143, v127, 16, 1
	v_add3_u32 v127, v127, v143, s75
	v_addc_co_u32_e32 v173, vcc, 0, v59, vcc
	global_store_short_d16_hi v[172:173], v127, off offset:1024
	v_min_f32_e64 v127, -v3, s12
	v_mul_f32_e32 v127, 0x3fb8aa3b, v127
	v_exp_f32_e32 v127, v127
	v_pk_add_f32 v[172:173], v[60:61], 1.0 op_sel_hi:[1,0] neg_lo:[1,0] neg_hi:[1,0]
	v_add_co_u32_e32 v58, vcc, s13, v58
	v_mul_f32_e32 v60, v172, v127
	v_bfe_u32 v127, v60, 16, 1
	v_add3_u32 v60, v60, v127, s75
	v_addc_co_u32_e32 v59, vcc, 0, v59, vcc
	global_store_short_d16_hi v[58:59], v60, off offset:1024
	v_max_f32_e32 v59, 0x358637bd, v61
	v_cmp_gt_f32_e32 vcc, s33, v59
	v_sub_f32_e32 v58, v0, v3
	v_lshlrev_b32_e32 v80, 16, v186
	v_cndmask_b32_e64 v60, 0, 32, vcc
	v_ldexp_f32 v59, v59, v60
	v_log_f32_e32 v59, v59
	v_lshlrev_b32_e32 v81, 16, v188
	v_mul_f32_e32 v80, 0xbfb8aa3b, v80
	v_mul_f32_e32 v81, 0xbfb8aa3b, v81
	v_mul_f32_e32 v60, 0x3f317217, v59
	v_fma_f32 v60, v59, s79, -v60
	v_fmac_f32_e32 v60, 0x3377d1cf, v59
	v_fmac_f32_e32 v60, 0x3f317217, v59
	v_cmp_lt_f32_e64 s[0:1], |v59|, s73
	v_exp_f32_e32 v80, v80
	v_exp_f32_e32 v81, v81
	v_cndmask_b32_e64 v59, v59, v60, s[0:1]
	v_cndmask_b32_e32 v60, 0, v211, vcc
	v_sub_f32_e32 v59, v59, v60
	v_add_f32_e32 v3, v3, v59
	v_mul_f32_e32 v59, 0x3fb8aa3b, v3
	v_exp_f32_e32 v59, v59
	v_lshlrev_b32_e32 v76, 16, v187
	v_mul_f32_e32 v139, 0x3db504f3, v76
	v_lshl_add_u64 v[76:77], s[46:47], 0, v[28:29]
	v_mul_f32_e32 v59, v129, v59
	v_bfe_u32 v60, v59, 16, 1
	v_add3_u32 v59, v59, v60, s75
	v_add_co_u32_e32 v60, vcc, s5, v64
	v_lshlrev_b32_e32 v70, 16, v189
	s_nop 3
	v_addc_co_u32_e32 v61, vcc, 0, v65, vcc
	global_store_short_d16_hi v[60:61], v59, off offset:1024
	v_min_f32_e64 v59, -v3, s12
	v_mul_f32_e32 v59, 0x3fb8aa3b, v59
	v_exp_f32_e32 v59, v59
	v_mul_f32_e32 v141, 0x3db504f3, v70
	v_mul_f32_e32 v58, 0x3fb8aa3b, v58
	v_exp_f32_e32 v58, v58
	v_mul_f32_e32 v59, v173, v59
	v_bfe_u32 v60, v59, 16, 1
	v_add3_u32 v59, v59, v60, s75
	v_add_co_u32_e32 v60, vcc, s13, v64
	v_lshl_add_u64 v[70:71], s[46:47], 0, v[24:25]
	s_nop 0
	v_addc_co_u32_e32 v61, vcc, 0, v65, vcc
	global_store_short_d16_hi v[60:61], v59, off offset:1024
	v_pk_add_f32 v[60:61], v[66:67], 1.0 op_sel_hi:[1,0]
	v_sub_f32_e32 v59, v0, v3
	v_mul_f32_e32 v59, 0x3fb8aa3b, v59
	v_exp_f32_e32 v59, v59
	v_lshl_add_u64 v[24:25], v[24:25], 0, 16
	v_rcp_f32_e32 v64, v61
	s_nop 0
	v_mul_f32_e32 v61, 1.0, v64
	v_pk_mul_f32 v[58:59], v[172:173], v[58:59]
	v_lshl_add_u64 v[28:29], v[28:29], 0, s[54:55]
	v_lshl_add_u64 v[32:33], v[32:33], 0, s[54:55]
	v_rcp_f32_e32 v64, v60
	s_nop 0
	v_mul_f32_e32 v60, 1.0, v64
	v_pk_fma_f32 v[60:61], v[6:7], v[60:61], v[4:5]
	s_nop 0
	v_max_f32_e32 v64, 0x358637bd, v60
	v_cmp_gt_f32_e32 vcc, s33, v64
	s_nop 1
	v_cndmask_b32_e64 v65, 0, 32, vcc
	v_ldexp_f32 v64, v64, v65
	v_log_f32_e32 v64, v64
	s_nop 0
	v_mul_f32_e32 v65, 0x3f317217, v64
	v_fma_f32 v65, v64, s79, -v65
	v_fmac_f32_e32 v65, 0x3377d1cf, v64
	v_fmac_f32_e32 v65, 0x3f317217, v64
	v_cmp_lt_f32_e64 s[0:1], |v64|, s73
	s_nop 1
	v_cndmask_b32_e64 v64, v64, v65, s[0:1]
	v_cndmask_b32_e32 v65, 0, v211, vcc
	v_sub_f32_e32 v64, v64, v65
	v_max_f32_e32 v65, 0x358637bd, v61
	v_cmp_gt_f32_e32 vcc, s33, v65
	v_add_f32_e32 v3, v3, v64
	v_mul_f32_e32 v64, 0x3fb8aa3b, v3
	v_cndmask_b32_e64 v66, 0, 32, vcc
	v_ldexp_f32 v65, v65, v66
	v_log_f32_e32 v65, v65
	v_exp_f32_e32 v64, v64
	v_pk_add_f32 v[60:61], v[60:61], 1.0 op_sel_hi:[1,0] neg_lo:[1,0] neg_hi:[1,0]
	v_mul_f32_e32 v66, 0x3f317217, v65
; DI bf16_t f2bf(float x) { unsigned u = __float_as_uint(x); u += 0x7fffu + ((u >> 16) & 1u); return (bf16_t)(u >> 16); }
; DI float bf2f(bf16_t b) { return __uint_as_float(((unsigned)b) << 16); }
; DI float sigmoidf_(float x) { return 1.f / (1.f + __expf(-x)); }
; DI void phase_prep(const P& p, int layer, float* ldsf) {
;     ...
;         for (int j = 0; j < 8; ++j) {
;           const int n = n8 * 8 + j;
;           float fl = bf2f(fl_[j]);
;           float f = lbv + (1.f - lbv) * sigmoidf_(fl);
;           G += __logf(fmaxf(f, 1e-6f));
;           float kk = 1.f - f;
;           qp[(long)(t0 + n) * 1024 + 512 + tid] = f2bf(bf2f(gq_[j]) * SCALE * __expf(G));
;           kp[(long)(t0 + n) * 1024 + 512 + tid] = f2bf(kk * __expf(fminf(-G, 80.f)));
;           kq8[j] = kk * __expf(G31 - G);
	v_fma_f32 v66, v65, s79, -v66
	v_fmac_f32_e32 v66, 0x3377d1cf, v65
	v_fmac_f32_e32 v66, 0x3f317217, v65
	v_cmp_lt_f32_e64 s[0:1], |v65|, s73
	v_mul_f32_e32 v64, v131, v64
	s_nop 0
	v_cndmask_b32_e64 v65, v65, v66, s[0:1]
	v_cndmask_b32_e32 v66, 0, v211, vcc
	v_sub_f32_e32 v66, v65, v66
	v_bfe_u32 v65, v64, 16, 1
	v_add3_u32 v67, v64, v65, s75
	v_add_co_u32_e32 v64, vcc, s5, v62
	s_nop 1
	v_addc_co_u32_e32 v65, vcc, 0, v63, vcc
	global_store_short_d16_hi v[64:65], v67, off offset:1024
	v_min_f32_e64 v64, -v3, s12
	v_mul_f32_e32 v64, 0x3fb8aa3b, v64
	v_exp_f32_e32 v64, v64
	v_add_co_u32_e32 v62, vcc, s13, v62
	v_mul_f32_e32 v64, v60, v64
	v_bfe_u32 v65, v64, 16, 1
	v_add3_u32 v64, v64, v65, s75
	v_addc_co_u32_e32 v63, vcc, 0, v63, vcc
	global_store_short_d16_hi v[62:63], v64, off offset:1024
	v_sub_f32_e32 v62, v0, v3
	v_add_f32_e32 v3, v3, v66
	v_mul_f32_e32 v63, 0x3fb8aa3b, v3
	v_exp_f32_e32 v63, v63
	v_mul_f32_e32 v62, 0x3fb8aa3b, v62
	v_exp_f32_e32 v62, v62
	v_mul_f32_e32 v63, v133, v63
	v_bfe_u32 v64, v63, 16, 1
	v_add3_u32 v63, v63, v64, s75
	v_add_co_u32_e32 v64, vcc, s5, v72
	s_nop 1
	v_addc_co_u32_e32 v65, vcc, 0, v73, vcc
	global_store_short_d16_hi v[64:65], v63, off offset:1024
	v_min_f32_e64 v63, -v3, s12
	v_mul_f32_e32 v63, 0x3fb8aa3b, v63
	v_exp_f32_e32 v63, v63
	s_nop 0
	v_mul_f32_e32 v63, v61, v63
	v_bfe_u32 v64, v63, 16, 1
	v_add3_u32 v63, v63, v64, s75
	v_add_co_u32_e32 v64, vcc, s13, v72
	s_nop 1
	v_addc_co_u32_e32 v65, vcc, 0, v73, vcc
	global_store_short_d16_hi v[64:65], v63, off offset:1024
	v_sub_f32_e32 v63, v0, v3
	v_mul_f32_e32 v63, 0x3fb8aa3b, v63
	v_exp_f32_e32 v63, v63
	s_nop 0
	v_pk_mul_f32 v[60:61], v[60:61], v[62:63]
	v_pk_add_f32 v[62:63], v[74:75], 1.0 op_sel_hi:[1,0]
	v_bfe_u32 v74, v59, 16, 1
	v_bfe_u32 v75, v58, 16, 1
	v_add3_u32 v58, v58, v75, s75
	v_rcp_f32_e32 v64, v63
	s_nop 0
	v_mul_f32_e32 v63, 1.0, v64
	s_nop 0
	v_rcp_f32_e32 v64, v62
	s_nop 0
	v_mul_f32_e32 v62, 1.0, v64
	v_pk_fma_f32 v[62:63], v[6:7], v[62:63], v[4:5]
	s_nop 0
	v_max_f32_e32 v64, 0x358637bd, v62
	v_cmp_gt_f32_e32 vcc, s33, v64
	s_nop 1
	v_cndmask_b32_e64 v65, 0, 32, vcc
	v_ldexp_f32 v64, v64, v65
	v_log_f32_e32 v64, v64
	s_nop 0
	v_mul_f32_e32 v65, 0x3f317217, v64
	v_fma_f32 v65, v64, s79, -v65
	v_fmac_f32_e32 v65, 0x3377d1cf, v64
	v_fmac_f32_e32 v65, 0x3f317217, v64
	v_cmp_lt_f32_e64 s[0:1], |v64|, s73
	s_nop 1
	v_cndmask_b32_e64 v64, v64, v65, s[0:1]
	v_cndmask_b32_e32 v65, 0, v211, vcc
	v_sub_f32_e32 v64, v64, v65
	v_max_f32_e32 v65, 0x358637bd, v63
	v_cmp_gt_f32_e32 vcc, s33, v65
	v_add_f32_e32 v3, v3, v64
	v_mul_f32_e32 v64, 0x3fb8aa3b, v3
	v_cndmask_b32_e64 v66, 0, 32, vcc
	v_ldexp_f32 v65, v65, v66
	v_log_f32_e32 v65, v65
	v_exp_f32_e32 v64, v64
	v_pk_add_f32 v[62:63], v[62:63], 1.0 op_sel_hi:[1,0] neg_lo:[1,0] neg_hi:[1,0]
	v_mul_f32_e32 v66, 0x3f317217, v65
	v_fma_f32 v66, v65, s79, -v66
	v_fmac_f32_e32 v66, 0x3377d1cf, v65
	v_fmac_f32_e32 v66, 0x3f317217, v65
	v_cmp_lt_f32_e64 s[0:1], |v65|, s73
	v_mul_f32_e32 v64, v135, v64
	s_nop 0
	v_cndmask_b32_e64 v65, v65, v66, s[0:1]
	v_cndmask_b32_e32 v66, 0, v211, vcc
	v_sub_f32_e32 v66, v65, v66
	v_bfe_u32 v65, v64, 16, 1
	v_add3_u32 v67, v64, v65, s75
	v_add_co_u32_e32 v64, vcc, s5, v68
	s_nop 1
	v_addc_co_u32_e32 v65, vcc, 0, v69, vcc
	global_store_short_d16_hi v[64:65], v67, off offset:1024
	v_min_f32_e64 v64, -v3, s12
	v_mul_f32_e32 v64, 0x3fb8aa3b, v64
	v_exp_f32_e32 v64, v64
	s_nop 0
	v_mul_f32_e32 v64, v62, v64
	v_bfe_u32 v65, v64, 16, 1
	v_add3_u32 v67, v64, v65, s75
	v_add_co_u32_e32 v64, vcc, s13, v68
	s_nop 1
	v_addc_co_u32_e32 v65, vcc, 0, v69, vcc
	global_store_short_d16_hi v[64:65], v67, off offset:1024
	v_sub_f32_e32 v64, v0, v3
	v_add_f32_e32 v3, v3, v66
	v_mul_f32_e32 v65, 0x3fb8aa3b, v3
	v_exp_f32_e32 v65, v65
	v_mul_f32_e32 v64, 0x3fb8aa3b, v64
	v_exp_f32_e32 v64, v64
	v_mul_f32_e32 v65, v137, v65
	v_bfe_u32 v66, v65, 16, 1
	v_add3_u32 v65, v65, v66, s75
	v_add_co_u32_e32 v66, vcc, s5, v78
	s_nop 1
	v_addc_co_u32_e32 v67, vcc, 0, v79, vcc
	global_store_short_d16_hi v[66:67], v65, off offset:1024
	v_min_f32_e64 v65, -v3, s12
	v_mul_f32_e32 v65, 0x3fb8aa3b, v65
	v_exp_f32_e32 v65, v65
; DI bf16_t f2bf(float x) { unsigned u = __float_as_uint(x); u += 0x7fffu + ((u >> 16) & 1u); return (bf16_t)(u >> 16); }
; DI float bf2f(bf16_t b) { return __uint_as_float(((unsigned)b) << 16); }
; DI float sigmoidf_(float x) { return 1.f / (1.f + __expf(-x)); }
; DI void phase_prep(const P& p, int layer, float* ldsf) {
;     ...
;         for (int j = 0; j < 8; ++j) {
;           const int n = n8 * 8 + j;
;           float fl = bf2f(fl_[j]);
;           float f = lbv + (1.f - lbv) * sigmoidf_(fl);
;           G += __logf(fmaxf(f, 1e-6f));
;           float kk = 1.f - f;
;           qp[(long)(t0 + n) * 1024 + 512 + tid] = f2bf(bf2f(gq_[j]) * SCALE * __expf(G));
;           kp[(long)(t0 + n) * 1024 + 512 + tid] = f2bf(kk * __expf(fminf(-G, 80.f)));
;           kq8[j] = kk * __expf(G31 - G);
;         }
;         store_t32(kppT + ((long)(c * 8 + 4 + hd) * 128 + d) * 32 + n8 * 8, kq8);
;       }
;       adec[(c * 8 + 4 + hd) * 128 + d] = __expf(G31);
	s_nop 0
	v_mul_f32_e32 v65, v63, v65
	v_bfe_u32 v66, v65, 16, 1
	v_add3_u32 v65, v65, v66, s75
	v_add_co_u32_e32 v66, vcc, s13, v78
	s_nop 1
	v_addc_co_u32_e32 v67, vcc, 0, v79, vcc
	global_store_short_d16_hi v[66:67], v65, off offset:1024
	v_sub_f32_e32 v65, v0, v3
	v_mul_f32_e32 v65, 0x3fb8aa3b, v65
	v_exp_f32_e32 v65, v65
	s_nop 0
	v_pk_mul_f32 v[62:63], v[62:63], v[64:65]
	v_pk_add_f32 v[64:65], v[80:81], 1.0 op_sel_hi:[1,0]
	s_nop 0
	s_nop 0
	v_rcp_f32_e32 v66, v65
	s_nop 0
	v_mul_f32_e32 v65, 1.0, v66
	s_nop 0
	v_rcp_f32_e32 v66, v64
	s_nop 0
	v_mul_f32_e32 v64, 1.0, v66
	v_pk_fma_f32 v[64:65], v[6:7], v[64:65], v[4:5]
	s_nop 0
	v_max_f32_e32 v66, 0x358637bd, v64
	v_cmp_gt_f32_e32 vcc, s33, v66
	s_nop 1
	v_cndmask_b32_e64 v67, 0, 32, vcc
	v_ldexp_f32 v66, v66, v67
	v_log_f32_e32 v66, v66
	s_nop 0
	v_mul_f32_e32 v67, 0x3f317217, v66
	v_fma_f32 v67, v66, s79, -v67
	v_fmac_f32_e32 v67, 0x3377d1cf, v66
	v_fmac_f32_e32 v67, 0x3f317217, v66
	v_cmp_lt_f32_e64 s[0:1], |v66|, s73
	s_nop 1
	v_cndmask_b32_e64 v66, v66, v67, s[0:1]
	v_cndmask_b32_e32 v67, 0, v211, vcc
	v_sub_f32_e32 v66, v66, v67
	v_max_f32_e32 v67, 0x358637bd, v65
	v_cmp_gt_f32_e32 vcc, s33, v67
	v_add_f32_e32 v3, v3, v66
	v_mul_f32_e32 v66, 0x3fb8aa3b, v3
	v_cndmask_b32_e64 v68, 0, 32, vcc
	v_ldexp_f32 v67, v67, v68
	v_log_f32_e32 v67, v67
	v_exp_f32_e32 v66, v66
	v_pk_add_f32 v[64:65], v[64:65], 1.0 op_sel_hi:[1,0] neg_lo:[1,0] neg_hi:[1,0]
	v_mul_f32_e32 v68, 0x3f317217, v67
	v_fma_f32 v68, v67, s79, -v68
	v_fmac_f32_e32 v68, 0x3377d1cf, v67
	v_fmac_f32_e32 v68, 0x3f317217, v67
	v_cmp_lt_f32_e64 s[0:1], |v67|, s73
	v_mul_f32_e32 v66, v139, v66
	s_nop 0
	v_cndmask_b32_e64 v67, v67, v68, s[0:1]
	v_cndmask_b32_e32 v68, 0, v211, vcc
	v_sub_f32_e32 v68, v67, v68
	v_bfe_u32 v67, v66, 16, 1
	v_add3_u32 v69, v66, v67, s75
	v_add_co_u32_e32 v66, vcc, s5, v76
	s_nop 1
	v_addc_co_u32_e32 v67, vcc, 0, v77, vcc
	global_store_short_d16_hi v[66:67], v69, off offset:1024
	v_min_f32_e64 v66, -v3, s12
	v_mul_f32_e32 v66, 0x3fb8aa3b, v66
	v_exp_f32_e32 v66, v66
	s_nop 0
	v_mul_f32_e32 v66, v64, v66
	v_bfe_u32 v67, v66, 16, 1
	v_add3_u32 v69, v66, v67, s75
	v_add_co_u32_e32 v66, vcc, s13, v76
	s_nop 1
	v_addc_co_u32_e32 v67, vcc, 0, v77, vcc
	global_store_short_d16_hi v[66:67], v69, off offset:1024
	v_sub_f32_e32 v66, v0, v3
	v_add_f32_e32 v3, v3, v68
	v_mul_f32_e32 v67, 0x3fb8aa3b, v3
	v_exp_f32_e32 v67, v67
	v_mul_f32_e32 v66, 0x3fb8aa3b, v66
	v_exp_f32_e32 v66, v66
	v_mul_f32_e32 v67, v141, v67
	v_bfe_u32 v68, v67, 16, 1
	v_add3_u32 v67, v67, v68, s75
	v_add_co_u32_e32 v68, vcc, s5, v170
	s_nop 1
	v_addc_co_u32_e32 v69, vcc, 0, v171, vcc
	global_store_short_d16_hi v[68:69], v67, off offset:1024
	v_min_f32_e64 v67, -v3, s12
	v_mul_f32_e32 v67, 0x3fb8aa3b, v67
	v_exp_f32_e32 v67, v67
	s_nop 0
	v_mul_f32_e32 v67, v65, v67
	v_bfe_u32 v68, v67, 16, 1
	v_add3_u32 v67, v67, v68, s75
	v_add_co_u32_e32 v68, vcc, s13, v170
	s_nop 1
	v_addc_co_u32_e32 v69, vcc, 0, v171, vcc
	global_store_short_d16_hi v[68:69], v67, off offset:1024
	v_sub_f32_e32 v67, v0, v3
	v_mul_f32_e32 v67, 0x3fb8aa3b, v67
	v_exp_f32_e32 v67, v67
	v_bfe_u32 v68, v63, 16, 1
	v_bfe_u32 v69, v62, 16, 1
	v_add3_u32 v62, v62, v69, s75
	v_pk_mul_f32 v[64:65], v[64:65], v[66:67]
	v_bfe_u32 v66, v61, 16, 1
	v_bfe_u32 v67, v60, 16, 1
	v_bfe_u32 v72, v65, 16, 1
	v_bfe_u32 v73, v64, 16, 1
	v_add3_u32 v64, v64, v73, s75
	v_add3_u32 v65, v65, v72, s75
	v_add3_u32 v63, v63, v68, s75
	v_add3_u32 v60, v60, v67, s75
	v_add3_u32 v61, v61, v66, s75
	v_add3_u32 v66, v59, v74, s75
	v_perm_b32 v59, v61, v60, s76
	v_perm_b32 v60, v63, v62, s76
	v_perm_b32 v61, v65, v64, s76
	v_perm_b32 v58, v66, v58, s76
	global_store_dwordx4 v[70:71], v[58:61], off
	s_cbranch_scc0 .LBB0_360
	v_mul_f32_e32 v0, 0x3fb8aa3b, v0
	v_exp_f32_e32 v0, v0
	v_add_u32_e32 v2, 0x200, v2
	v_readlane_b32 s2, v252, 59
	s_lshl_b64 s[0:1], s[28:29], 1
	v_ashrrev_i32_e32 v3, 31, v2
	v_readlane_b32 s3, v252, 60
	v_lshl_add_u64 v[4:5], v[160:161], 0, s[0:1]
	v_lshl_add_u64 v[6:7], v[162:163], 0, s[0:1]
	v_lshl_add_u64 v[2:3], v[2:3], 2, s[2:3]
	s_mov_b32 s2, 4
	s_mov_b32 s4, 0x6000000
	global_store_dword v[2:3], v0, off
